# w_o and w_down bf16 weight transposes moved from phase 3 into phase 2 and co-scheduled: half the workgroups stream them before their attention units, half after the column-max pass
# speedup vs baseline: 1.0038x; 1.0038x over previous
; #define LAS __attribute__((address_space(3)))
; __device__ __forceinline__ void ph_transpose(const TrJob job, LAS unsigned* scr, int gw, int NGW, int lane) {
;     const float* __restrict__ W = job.W; bf16_t* __restrict__ WT = job.WT; const float* __restrict__ ks = job.kscale;
;     const int ngrp = job.nrows / 64, nitems = (job.K / 64) * ngrp;
;     for (int item = gw; item < nitems; item += NGW) {
;         const int kb = item / ngrp, gq = item % ngrp, k0 = 64 * kb, r0 = 64 * gq, sb = srcbase_of(job.kind, r0);
;         const int n4 = (lane & 15) * 4; const bool inb = sb + n4 < job.N;
; __global__ void __launch_bounds__(512, 2) k_fwd(Args a_unused) {
;     ...
;     if (IN(2)) { PH_IDS();
;     ...
;         j.W = ap->in[12]; j.WT = (bf16_t*)(ws + WS_WO); j.kscale = ap->in[11]; j.K = DM; j.N = DM; j.nrows = DM; j.kind = 0; j.kxor = 2048; j.kscale_n = 2048; ph_transpose(j, scr, gw, NGW, lane);
.LBB0_495:
	s_cmp_lt_i32 s76, 3
	s_cselect_b64 s[4:5], -1, 0
	s_and_b64 s[44:45], s[4:5], s[6:7]
	s_andn2_b64 vcc, exec, s[44:45]
	s_cbranch_vccnz .LBB0_694
	s_mov_b64 s[100:101], s[44:45]
	s_bitcmp1_b32 s2, 3
	s_cbranch_scc1 .Lbw_skip_early
	s_mov_b32 s99, 1
.Lbw_entry:
	s_mov_b64 s[22:23], s[92:93]
	s_load_dwordx2 s[20:21], s[22:23], 0xb8
	v_mov_b32_e32 v70, v0
	v_readfirstlane_b32 s1, v0
	s_waitcnt lgkmcnt(0)
	s_ashr_i32 s1, s1, 6
	s_lshl_b32 s3, s2, 3
	s_add_i32 s3, s1, s3
	s_lshl_b32 s1, s1, 14
	s_lshl_b32 s34, s74, 3
	s_add_i32 s35, s1, 0
	v_and_b32_e32 v81, 63, v70
	s_cmpk_lt_i32 s3, 0x1000
	s_movk_i32 s4, 0x1000
	s_cselect_b64 s[24:25], -1, 0
	s_cmpk_gt_i32 s3, 0xfff
	v_lshlrev_b32_e32 v89, 2, v81
	v_lshrrev_b32_e32 v83, 3, v81
	v_lshrrev_b32_e32 v1, 4, v81
	v_and_b32_e32 v87, 7, v70
	s_cbranch_scc1 .Lbw_mid
	s_load_dwordx4 s[8:11], s[22:23], 0x58
	v_and_b32_e32 v71, 60, v89
	v_mov_b32_e32 v2, 0
	v_lshlrev_b32_e32 v4, 2, v71
	v_mov_b32_e32 v5, v2
	s_waitcnt lgkmcnt(0)
	v_lshl_add_u64 v[72:73], s[10:11], 0, v[4:5]
	s_cmp_lg_u64 s[8:9], 0
	v_add_u32_e32 v3, s35, v4
	v_lshlrev_b32_e32 v4, 4, v87
	s_cselect_b64 s[6:7], -1, 0
	v_lshl_add_u64 v[4:5], s[20:21], 0, v[4:5]
	s_mov_b64 s[10:11], 0x4e00000
	s_lshl_b32 s5, s3, 6
	v_lshl_add_u64 v[74:75], v[4:5], 0, s[10:11]
	s_movk_i32 s1, 0x410
	v_mov_b32_e32 v4, s35
	v_or_b32_e32 v5, s5, v83
	v_mad_u32_u24 v91, v87, s1, v4
	v_mul_u32_u24_e32 v4, 0x104, v1
	v_lshlrev_b32_e32 v5, 1, v5
	v_lshlrev_b32_e32 v6, 1, v83
	v_and_b32_e32 v85, 6, v83
	s_sub_i32 s16, 0, s5
	s_lshl_b32 s17, s34, 6
	v_or_b32_e32 v93, 0x70, v5
	s_lshl_b32 s18, s34, 7
	v_lshl_or_b32 v95, s3, 7, v6
	v_or_b32_e32 v97, 0x50, v5
	v_or_b32_e32 v99, 16, v5
	v_or_b32_e32 v101, 48, v5
	s_movk_i32 s19, 0x800
	v_add_u32_e32 v103, v3, v4
	s_movk_i32 s26, 0xffe3
	s_mov_b32 s27, s3
	s_branch .Lbw_757

; #define LAS __attribute__((address_space(3)))
; __device__ __forceinline__ void ph_transpose(const TrJob job, LAS unsigned* scr, int gw, int NGW, int lane) {
;     const float* __restrict__ W = job.W; bf16_t* __restrict__ WT = job.WT; const float* __restrict__ ks = job.kscale;
;     const int ngrp = job.nrows / 64, nitems = (job.K / 64) * ngrp;
;     for (int item = gw; item < nitems; item += NGW) {
;         const int kb = item / ngrp, gq = item % ngrp, k0 = 64 * kb, r0 = 64 * gq, sb = srcbase_of(job.kind, r0);
;         const int n4 = (lane & 15) * 4; const bool inb = sb + n4 < job.N;
; __global__ void __launch_bounds__(512, 2) k_fwd(Args a_unused) {
;     ...
;         j.W = ap->in[17]; j.WT = (bf16_t*)(ws + WS_WDN); j.kscale = nullptr; j.K = DFF; j.N = DM; j.nrows = DM; j.kind = 0; j.kxor = 0; j.kscale_n = 0; ph_transpose(j, scr, gw, NGW, lane);
.Lbw_mid:
	v_lshrrev_b32_e32 v85, 2, v81
	v_and_b32_e32 v91, 3, v70
	s_cmpk_gt_i32 s3, 0x2aff
	s_cbranch_scc1 .Lbw_end
	s_load_dwordx2 s[4:5], s[22:23], 0x88
	v_and_b32_e32 v76, 60, v89
	v_mov_b32_e32 v3, 0
	v_lshlrev_b32_e32 v2, 2, v76
	v_add_u32_e32 v4, s35, v2
	s_waitcnt lgkmcnt(0)
	v_lshl_add_u64 v[68:69], s[4:5], 0, v[2:3]
	v_lshlrev_b32_e32 v2, 4, v87
	v_lshl_add_u64 v[2:3], s[20:21], 0, v[2:3]
	s_mov_b64 s[4:5], 0x11a00000
	v_lshl_add_u64 v[70:71], v[2:3], 0, s[4:5]
	s_movk_i32 s1, 0x410
	v_mov_b32_e32 v2, s35
	v_mad_u32_u24 v78, v87, s1, v2
	s_lshl_b32 s1, s3, 6
	v_or_b32_e32 v3, s1, v83
	v_lshlrev_b32_e32 v3, 1, v3
	s_mul_i32 s6, s3, 0xac000
	v_or_b32_e32 v79, 0x70, v3
	v_or_b32_e32 v82, 0x50, v3
	v_or_b32_e32 v84, 16, v3
	v_or_b32_e32 v86, 48, v3
	s_movk_i32 s7, 0x2b00
	v_mov_b32_e32 v3, s6
	v_mul_u32_u24_e32 v2, 0x104, v1
	v_lshlrev_b32_e32 v5, 1, v83
	v_mad_u32_u24 v3, v83, s7, v3
	v_and_b32_e32 v77, 6, v83
	s_sub_i32 s4, 0, s1
	s_lshl_b32 s5, s34, 6
	s_lshl_b32 s10, s34, 7
	v_lshl_or_b32 v80, s3, 7, v5
	v_add_u32_e32 v87, 0x56000, v3
	s_mul_i32 s11, s34, 0xac000
	s_movk_i32 s12, 0x1000
	v_add_u32_e32 v88, v4, v2
	s_movk_i32 s13, 0xffe3
	s_mov_b32 s16, s3
	s_branch .Lbw_919

; #define LAS __attribute__((address_space(3)))
; __device__ __forceinline__ s16x4 lds_tr4_64(LAS const unsigned char* tile, unsigned rowbase, unsigned c32, unsigned lane) {
;     const unsigned blk = (lane >> 4) & 1, q = (lane & 15) >> 2, p = lane & 3;
;     LAS const unsigned char* a = tile + off64(rowbase + q, 4 * c32 + 2 * blk + (p >> 1)) + 8 * (p & 1);
;     return __builtin_bit_cast(s16x4, __builtin_amdgcn_ds_read_tr16_b64_v4i16((LAS s16x4*)a));
; }
; __device__ __forceinline__ void attn_unit(LAS unsigned char* lds, const bf16_t* Q, const bf16_t* Kb, const bf16_t* V, const float* sinks, bf16_t* MIX, int nb, int kv, int tid, int lane, int wave) {
;     const int hq = kv * 8 + wave, h = lane >> 5, l31 = lane & 31;
;     bf16x8 Qf[4];
; #pragma unroll
;     for (int ks = 0; ks < 4; ++ks) Qf[ks] = *(const bf16x8*)(Q + (size_t)(128 * nb + l31) * 2048 + hq * 64 + 16 * ks + 8 * h);
; #pragma unroll
;     for (int j = 0; j < 4; ++j) { const int idx = tid + 512 * j, row = idx >> 3, ch = idx & 7; int tok = 128 * (nb - 1) + row; tok = tok < 0 ? 0 : tok;
;         const size_t go = (size_t)tok * 256 + kv * 64 + ch * 8;
;         *(LAS u32x4*)(lds + ATT_K + off64(row, ch)) = *(const u32x4*)(Kb + go);
;         *(LAS u32x4*)(lds + ATT_V + off64(row, ch)) = *(const u32x4*)(V + go); }
;     __syncthreads();
;     const float sink = sinks[hq];
;     LAS const unsigned char* kt_ = lds + ATT_K; LAS const unsigned char* vt_ = lds + ATT_V;
; __global__ void __launch_bounds__(512, 2) k_fwd(Args a_unused) {
;     ...
;         for (int u = c; u < 512; u += G) attn_unit(lds, (const bf16_t*)(ws + WS_Q), (const bf16_t*)(ws + WS_K), (const bf16_t*)(ws + WS_V), ap->in[5], (bf16_t*)(ws + WS_MIX), u >> 2, u & 3, tid, lane, wave);
.Lbw_end:
	s_cmp_eq_u32 s99, 2
	s_cbranch_scc1 .Lbw_ret2
	s_barrier
.Lbw_skip_early:
	s_mov_b64 s[44:45], s[100:101]
	s_mov_b64 s[86:87], s[92:93]
	v_writelane_b32 v254, s44, 0
	s_load_dwordx2 s[84:85], s[86:87], 0xb8
	v_mov_b32_e32 v107, v0
	v_writelane_b32 v254, s45, 1
	v_writelane_b32 v254, s96, 2
	s_mov_b64 s[82:83], s[76:77]
	v_readfirstlane_b32 s4, v107
	v_writelane_b32 v254, s97, 3
	v_and_b32_e32 v106, 63, v107
	s_ashr_i32 s75, s4, 6
	v_writelane_b32 v254, s94, 4
	s_mov_b64 s[76:77], s[92:93]
	s_cmpk_gt_i32 s2, 0x1ff
	v_bfe_u32 v109, v107, 2, 2
	v_bfe_u32 v110, v107, 1, 1
	v_lshrrev_b32_e32 v108, 5, v106
	v_lshrrev_b32_e32 v111, 3, v107
	v_lshlrev_b32_e32 v1, 3, v106
	v_writelane_b32 v254, s95, 5
	s_cbranch_scc1 .LBB0_503
	v_ashrrev_i32_e32 v113, 3, v107
	v_xor_b32_e32 v5, v113, v107
	v_lshlrev_b32_e32 v4, 7, v113
	v_lshlrev_b32_e32 v5, 4, v5
	s_movk_i32 s1, 0x70
	v_and_or_b32 v5, v5, s1, v4
	v_add_u32_e32 v4, 0x200, v107
	v_ashrrev_i32_e32 v114, 3, v4
	v_xor_b32_e32 v6, v114, v107
	v_lshlrev_b32_e32 v4, 7, v114
	v_lshlrev_b32_e32 v6, 4, v6
	v_and_or_b32 v6, v6, s1, v4
	v_add_u32_e32 v4, 0x400, v107
	v_ashrrev_i32_e32 v115, 3, v4
	v_xor_b32_e32 v7, v115, v107
	v_lshlrev_b32_e32 v4, 7, v115
	v_lshlrev_b32_e32 v7, 4, v7
	v_and_or_b32 v7, v7, s1, v4
	v_add_u32_e32 v4, 0x600, v107
	v_ashrrev_i32_e32 v116, 3, v4
	v_xor_b32_e32 v8, v116, v107
	v_lshlrev_b32_e32 v4, 7, v116
	v_lshlrev_b32_e32 v8, 4, v8
	v_and_or_b32 v8, v8, s1, v4
	v_lshlrev_b32_e32 v4, 2, v108
	v_and_b32_e32 v112, 31, v107
	v_or_b32_e32 v16, 2, v4
	s_waitcnt lgkmcnt(0)
	v_cmp_gt_u32_e64 s[10:11], v16, v112
	v_or_b32_e32 v16, 3, v4
	v_cmp_gt_u32_e64 s[12:13], v16, v112
	v_or_b32_e32 v16, 8, v4
	v_cmp_gt_u32_e64 s[14:15], v16, v112
	v_or_b32_e32 v16, 9, v4
	v_cmp_gt_u32_e64 s[16:17], v16, v112
	v_or_b32_e32 v16, 10, v4
	v_cmp_gt_u32_e64 s[18:19], v16, v112
	v_or_b32_e32 v16, 11, v4
	v_cmp_gt_u32_e64 s[20:21], v16, v112
	v_or_b32_e32 v16, 16, v4
	v_cmp_gt_u32_e64 s[22:23], v16, v112
	v_or_b32_e32 v16, 17, v4
	v_mbcnt_lo_u32_b32 v11, -1, 0
	v_cmp_gt_u32_e64 s[24:25], v16, v112
	v_or_b32_e32 v16, 18, v4
	v_mbcnt_hi_u32_b32 v11, -1, v11
	v_cmp_gt_u32_e64 s[26:27], v16, v112
	v_or_b32_e32 v16, 19, v4
	v_and_b32_e32 v13, 64, v11
	v_cmp_gt_u32_e64 s[28:29], v16, v112
	v_or_b32_e32 v16, 24, v4
	v_xor_b32_e32 v12, 32, v11
	v_add_u32_e32 v13, 64, v13
	v_cmp_gt_u32_e64 s[30:31], v16, v112
	v_or_b32_e32 v16, 25, v4
	v_cmp_lt_i32_e32 vcc, v12, v13
	v_cmp_gt_u32_e64 s[34:35], v16, v112
	v_or_b32_e32 v16, 26, v4
	v_cndmask_b32_e32 v11, v11, v12, vcc
	v_cmp_gt_u32_e64 s[36:37], v16, v112
	v_or_b32_e32 v16, 27, v4
	s_add_u32 s88, s84, 0x31a00000
	v_and_b32_e32 v10, 7, v107
	v_lshlrev_b32_e32 v117, 2, v11
	v_and_or_b32 v11, v111, 2, v110
	v_cmp_gt_u32_e64 s[38:39], v16, v112
	v_or_b32_e32 v16, v4, v109
	s_addc_u32 s89, s85, 0
	s_load_dwordx2 s[94:95], s[86:87], 0x28
	v_lshlrev_b32_e32 v9, 7, v112
	v_bitop3_b32 v14, v108, v10, 2 bitop3:0x36
	v_bitop3_b32 v15, v108, v10, 4 bitop3:0x36
	v_bitop3_b32 v10, v108, v10, 6 bitop3:0x36
	v_bitop3_b32 v17, v4, v11, v109 bitop3:0x36
	v_bitop3_b32 v11, v11, v16, 4 bitop3:0x36
	v_lshlrev_b32_e32 v16, 7, v109
	s_add_u32 s90, s84, 0x35a00000
	v_and_b32_e32 v12, 8, v1
	v_lshlrev_b32_e32 v11, 4, v11
	v_lshl_or_b32 v16, v108, 9, v16
	v_lshl_or_b32 v10, v10, 4, v9
	s_addc_u32 s91, s85, 0
	v_lshlrev_b32_e32 v2, 3, v108
	v_lshlrev_b32_e32 v3, 3, v107
	v_bitop3_b32 v13, v108, v107, 7 bitop3:0x78
	v_lshlrev_b32_e32 v17, 4, v17
	v_or3_b32 v11, v16, v11, v12
	v_add_u32_e32 v120, 0, v10
	v_lshl_or_b32 v10, v15, 4, v9
	s_add_u32 s92, s84, 0x36200000
	v_mov_b32_e32 v99, 0
	v_and_b32_e32 v3, 56, v3
	v_add_u32_e32 v118, 0, v11
	v_or3_b32 v11, v16, v17, v12
	v_add_u32_e32 v121, 0, v10
	v_lshl_or_b32 v10, v14, 4, v9
	v_lshl_or_b32 v9, v13, 4, v9
	v_lshlrev_b32_e32 v100, 1, v2
	s_addc_u32 s93, s85, 0
	v_cmp_gt_u32_e64 s[6:7], v4, v112
	v_cmp_ge_u32_e64 s[8:9], v4, v112
	v_cmp_lt_u32_e64 s[40:41], v4, v112
	v_add_u32_e32 v119, 0, v11
	v_add_u32_e32 v122, 0, v10
	v_add_u32_e32 v123, 0, v9
	v_mov_b32_e32 v102, v100
	v_mov_b32_e32 v103, v99
	v_lshlrev_b32_e32 v124, 1, v3
	v_add_u32_e32 v125, 0, v5
	v_add_u32_e32 v126, 0, v6
	v_add_u32_e32 v127, 0, v7
	v_add_u32_e32 v128, 0, v8
	v_lshlrev_b32_e32 v98, 1, v4
	v_mov_b32_e32 v129, 0xf149f2ca
	s_mov_b32 s3, s2
	s_branch .LBB0_499

; #define SEAM(k) do { if (IN(k) && IN((k) + 1)) xcd_barrier(bar); } while (0)
; __global__ void __launch_bounds__(512, 2) k_fwd(Args a_unused) {
;     ...
;     if (IN(2)) { PH_IDS();
;         ph_colmax(ap->in[14], ap->in[13], DM, 2 * DFF, (unsigned*)ctl + CW_CMAX_UP, gw, NGW, lane);
;         ph_colmax(ap->in[18], nullptr, DM, DM, (unsigned*)ctl + CW_CMAX_G, gw, NGW, lane);
;     }
;     SEAM(2);
.Lp2_cm_end:
	s_bitcmp1_b32 s2, 3
	s_cbranch_scc0 .LBB0_694
	s_mov_b32 s99, 2
	s_branch .Lbw_entry
.Lbw_ret2:
	s_mov_b64 s[44:45], s[100:101]

; #define LAS __attribute__((address_space(3)))
; __global__ void __launch_bounds__(512, 2) k_fwd(Args a_unused) {
;     ...
;         LAS unsigned* scr = (LAS unsigned*)(lds + wave * 16384);
;         TrJob j; j.pad = 0; j.qmax = nullptr;
;         j.W = ap->in[12]; j.WT = (bf16_t*)(ws + WS_WO); j.kscale = ap->in[11]; j.K = DM; j.N = DM; j.nrows = DM; j.kind = 0; j.kxor = 2048; j.kscale_n = 2048; ph_transpose(j, scr, gw, NGW, lane);
.LBB0_754:
	s_or_b64 exec, exec, s[6:7]
	s_ashr_i32 s1, s1, 6
	s_lshl_b32 s3, s2, 3
	s_add_i32 s3, s1, s3
	s_lshl_b32 s1, s1, 14
	s_lshl_b32 s34, s74, 3
	s_add_i32 s35, s1, 0
	v_and_b32_e32 v81, 63, v70
	s_cmpk_lt_i32 s3, 0x1000
	s_movk_i32 s4, 0x1000
	s_cselect_b64 s[24:25], -1, 0
	s_cmpk_gt_i32 s3, 0xfff
	v_lshlrev_b32_e32 v89, 2, v81
	v_lshrrev_b32_e32 v83, 3, v81
	v_lshrrev_b32_e32 v1, 4, v81
	v_and_b32_e32 v87, 7, v70
	s_branch .LBB0_839

; __global__ void __launch_bounds__(512, 2) k_fwd(Args a_unused) {
;     ...
;         j.W = ap->in[17]; j.WT = (bf16_t*)(ws + WS_WDN); j.kscale = nullptr; j.K = DFF; j.N = DM; j.nrows = DM; j.kind = 0; j.kxor = 0; j.kscale_n = 0; ph_transpose(j, scr, gw, NGW, lane);
.LBB0_916:
	s_cmpk_gt_i32 s3, 0x2aff
	s_branch .LBB0_967
